# attention/pool units permuted and gate-tile queues split per XCD so every producer of a row panel runs on the XCD that consumes it; grid barrier after the attention phase replaced by the XCD-local bar
# speedup vs baseline: 1.0767x; 1.0429x over previous
.LBB0_215:
	s_andn2_b64 vcc, exec, s[0:1]
	s_cbranch_vccnz .LBB0_276
	s_cmpk_gt_i32 s74, 0x3bf
	v_ashrrev_i32_e32 v97, 1, v124
	v_lshlrev_b32_e32 v96, 3, v124
	s_cbranch_scc1 .LBB0_252
	v_bfe_u32 v0, v124, 2, 4
	v_bfe_u32 v3, v124, 5, 1
	v_lshl_or_b32 v0, v126, 5, v0
	s_waitcnt lgkmcnt(0)
	v_lshrrev_b32_e32 v1, 4, v124
	v_lshrrev_b32_e32 v4, 2, v124
	v_xor_b32_e32 v2, v1, v124
	v_ashrrev_i32_e32 v1, 31, v0
	v_bitop3_b32 v4, v3, v4, 3 bitop3:0x78
	v_and_b32_e32 v98, 31, v124
	v_lshlrev_b64 v[100:101], 10, v[0:1]
	v_lshlrev_b32_e32 v1, 3, v2
	v_lshlrev_b32_e32 v0, 5, v0
	v_lshlrev_b32_e32 v107, 4, v4
	v_lshlrev_b32_e32 v4, 6, v124
	s_mov_b32 s0, 0x3ffffc0
	v_ashrrev_i32_e32 v104, 3, v124
	s_lshl_b32 s13, s12, 2
	v_and_b32_e32 v2, 24, v1
	v_ashrrev_i32_e32 v1, 31, v0
	v_and_b32_e32 v119, 0x17c0, v4
	v_and_or_b32 v4, v97, s0, v98
	s_lshl_b32 s14, s12, 9
	v_ashrrev_i32_e32 v105, 31, v104
	v_add_u32_e32 v112, 32, v104
	s_movk_i32 s0, 0x90
	s_lshl_b32 s15, s12, 3
	s_lshl_b32 s16, s12, 1
	s_movk_i32 s9, 0xc00
	v_lshlrev_b64 v[108:109], 8, v[104:105]
	v_lshlrev_b64 v[110:111], 9, v[104:105]
	v_mul_lo_u32 v105, v104, s0
	v_mad_i64_i32 v[130:131], s[0:1], v104, s9, 0
	v_mad_i64_i32 v[132:133], s[0:1], v112, s9, 0
	s_add_u32 s17, s2, 0x142ce000
	v_lshl_add_u64 v[0:1], v[0:1], 1, s[2:3]
	v_lshlrev_b32_e32 v116, 1, v2
	s_addc_u32 s18, s3, 0
	v_lshl_add_u64 v[0:1], v[0:1], 0, v[116:117]
	s_mov_b64 s[0:1], 0x964e000
	v_lshl_add_u64 v[134:135], v[0:1], 0, s[0:1]
	s_add_u32 s0, s2, 0x148ce000
	s_addc_u32 s1, s3, 0
	s_add_u32 s19, s2, 0x133ce000
	s_addc_u32 s20, s3, 0
	s_add_u32 s21, s2, 0x13bce000
	s_addc_u32 s22, s3, 0
	s_add_u32 s36, s2, 0x12cce000
	s_addc_u32 s37, s3, 0
	s_add_u32 s23, s2, 0x132ce000
	s_addc_u32 s34, s3, 0
	s_add_u32 s35, s2, 0x13ace000
	s_addc_u32 s40, s3, 0
	s_add_u32 s38, s2, 0x126ce000
	s_addc_u32 s39, s3, 0
	s_add_u32 s41, s2, 0x137ce000
	s_addc_u32 s42, s3, 0
	v_lshlrev_b32_e32 v0, 6, v97
	s_add_u32 s43, s2, 0x13fce000
	v_and_b32_e32 v106, 56, v96
	v_ashrrev_i32_e32 v113, 31, v112
	v_and_b32_e32 v0, 0x1000, v0
	s_addc_u32 s80, s3, 0
	v_bfe_u32 v5, v124, 2, 2
	v_lshlrev_b32_e32 v121, 6, v4
	v_lshlrev_b32_e32 v102, 3, v3
	v_lshlrev_b64 v[114:115], 8, v[112:113]
	v_lshlrev_b64 v[128:129], 9, v[112:113]
	v_lshl_add_u32 v113, v106, 1, v105
	v_and_b32_e32 v4, -8, v124
	v_lshlrev_b32_e32 v163, 4, v3
	v_lshl_or_b32 v116, v3, 8, v0
	s_add_u32 s81, s2, 0x134ce000
	v_and_b32_e32 v0, 7, v124
	s_movk_i32 s8, 0xffe0
	v_bitop3_b32 v5, v3, v5, 2 bitop3:0x36
	v_sub_u32_e32 v158, 0, v4
	v_sub_u32_e32 v159, v113, v4
	v_lshlrev_b32_e32 v122, 2, v3
	v_mul_u32_u24_e32 v160, 0x44, v98
	v_sub_u32_e32 v4, v163, v102
	s_addc_u32 s64, s3, 0
	v_lshlrev_b32_e32 v138, 4, v0
	v_bfi_b32 v0, s8, v97, v124
	v_lshlrev_b32_e32 v103, 4, v5
	v_and_b32_e32 v125, 0x5f, v124
	v_and_b32_e32 v157, 0xffffffe0, v97
	v_lshl_add_u32 v165, v160, 1, v4
	v_mov_b64_e32 v[4:5], s[2:3]
	s_add_u32 s65, s2, 0x13cce000
	v_sub_u32_e32 v0, v0, v122
	v_lshlrev_b32_e32 v99, 11, v126
	v_or_b32_e32 v156, 32, v125
	v_mul_u32_u24_e32 v161, 0x90, v98
	v_add_u32_e32 v162, 0x1000, v157
	v_sub_u32_e32 v164, 0, v102
	v_add_u32_e32 v166, 0x1100, v165
	v_lshl_add_u64 v[136:137], s[0:1], 0, v[116:117]
	s_addc_u32 s66, s3, 0
	v_mov_b32_e32 v139, v117
	v_lshl_add_u64 v[140:141], s[2:3], 0, v[108:109]
	v_lshl_add_u64 v[142:143], s[2:3], 0, v[110:111]
	v_add_u32_e32 v167, 0x17f, v0
	v_mad_i64_i32 v[144:145], s[8:9], v104, s9, v[4:5]
	v_lshlrev_b32_e32 v146, 1, v2
	s_mov_b32 s99, s74
	s_branch .LBB0_219
.LBB0_218:
	s_load_dword s8, s[96:97], 0x0
	s_waitcnt lgkmcnt(0)
	s_add_i32 s99, s8, s99
	s_cmpk_lt_i32 s99, 0x3c0
	s_cbranch_scc0 .LBB0_252
.LBB0_219:
	s_mov_b32 s67, s99
	s_cmpk_lt_i32 s99, 0x100
	s_cbranch_scc1 .Lpi_done
	s_cmpk_lt_i32 s99, 0x300
	s_cbranch_scc0 .Lpi_pool
	s_and_b32 s8, s99, 7
	s_bfe_u32 s9, s99, 0x50003
	s_lshr_b32 s11, s9, 3
	s_lshl_b32 s11, s11, 2
	s_lshr_b32 s50, s8, 1
	s_or_b32 s11, s11, s50
	s_lshl_b32 s11, s11, 4
	s_and_b32 s9, s9, 7
	s_lshl_b32 s9, s9, 1
	s_or_b32 s11, s11, s9
	s_and_b32 s8, s8, 1
	s_or_b32 s11, s11, s8
	s_and_b32 s67, s99, 0x300
	s_or_b32 s67, s67, s11
	s_branch .Lpi_done
.Lpi_pool:
	s_add_i32 s9, s99, 0xfffffd00
	s_and_b32 s8, s9, 7
	s_lshr_b32 s9, s9, 3
	s_lshr_b32 s11, s9, 2
	s_lshl_b32 s11, s11, 3
	s_or_b32 s11, s11, s8
	s_lshl_b32 s11, s11, 2
	s_and_b32 s9, s9, 3
	s_or_b32 s11, s11, s9
	s_add_i32 s67, s11, 0x300

.LBB0_252:
	s_lshl_b32 s30, s12, 6
	s_lshl_b64 s[0:1], s[30:31], 2
	s_add_u32 s0, s2, s0
	s_addc_u32 s1, s3, s1
	s_add_u32 s0, s0, 0x3840
	s_addc_u32 s1, s1, 0
	s_load_dword s98, s[96:97], 0x0
	v_readlane_b32 s99, v255, 53
	s_waitcnt lgkmcnt(0)
	s_cmp_eq_u32 s98, 0x200
	s_cselect_b32 s98, 1, 0
	s_cmp_eq_u32 s99, 0
	s_cselect_b32 s98, s98, 0
	s_and_b32 s99, s74, 7
	s_cmp_eq_u32 s98, 0
	s_cbranch_scc1 .Lgq_a
	s_lshl_b32 s13, s99, 5
	s_add_u32 s0, s0, s13
	s_addc_u32 s1, s1, 0
.Lgq_a:
	v_cmp_eq_u32_e64 s[36:37], 0, v124
	s_waitcnt vmcnt(0) lgkmcnt(0)
	s_barrier
	s_and_saveexec_b64 s[8:9], s[36:37]
	s_mov_b64 s[66:67], 0x2400
	s_cbranch_execz .LBB0_256
	s_mov_b64 s[14:15], exec
	v_mbcnt_lo_u32_b32 v0, s14, 0
	v_mbcnt_hi_u32_b32 v0, s15, v0
	v_cmp_eq_u32_e32 vcc, 0, v0
	s_and_saveexec_b64 s[10:11], vcc
	s_cbranch_execz .LBB0_255
	s_bcnt1_i32_b64 s13, s[14:15]
	v_mov_b32_e32 v1, s13
	global_atomic_add v1, v117, v1, s[0:1] sc0

.LBB0_256:
	s_or_b64 exec, exec, s[8:9]
	s_mov_b64 s[8:9], src_shared_base
	v_mov_b32_e32 v121, s9
	s_waitcnt lgkmcnt(0)
	s_barrier
	flat_load_dword v0, v[120:121] sc0 sc1
	s_waitcnt vmcnt(0)
	s_cmp_eq_u32 s98, 0
	s_cbranch_scc1 .Lgq_skip1
	v_mul_u32_u24_e32 v1, 0xaaab, v0
	v_lshrrev_b32_e32 v1, 18, v1
	v_mul_u32_u24_e32 v2, 6, v1
	v_sub_u32_e32 v2, v0, v2
	v_mul_u32_u24_e32 v1, 48, v1
	v_lshl_add_u32 v1, v2, 3, v1
	v_add_u32_e32 v1, s99, v1
	v_add_u32_e32 v2, 0x600, v0
	s_movk_i32 s13, 0xc0
	v_cmp_gt_u32_e64 s[8:9], s13, v0
	s_nop 1
	v_cndmask_b32_e64 v0, v2, v1, s[8:9]
.Lgq_skip1:
	s_movk_i32 s8, 0x600
	s_waitcnt lgkmcnt(0)
	v_cmp_gt_u32_e32 vcc, s8, v0
	s_and_saveexec_b64 s[8:9], vcc
	s_cbranch_execz .LBB0_275
	v_bfe_u32 v3, v124, 2, 4
	v_lshl_or_b32 v6, v126, 5, v3
	s_mul_i32 s10, s12, 0xf00000
	v_lshrrev_b32_e32 v3, 4, v124
	v_ashrrev_i32_e32 v7, 31, v6
	s_mul_hi_u32 s11, s12, 0xf00000
	s_add_u32 s10, s2, s10
	v_xor_b32_e32 v3, v3, v124
	v_lshlrev_b64 v[8:9], 6, v[6:7]
	v_lshlrev_b32_e32 v6, 5, v6
	s_addc_u32 s11, s3, s11
	v_lshlrev_b32_e32 v3, 4, v3
	v_ashrrev_i32_e32 v7, 31, v6
	v_and_b32_e32 v116, 48, v3
	v_lshl_add_u64 v[6:7], v[6:7], 1, s[10:11]
	v_bfe_u32 v1, v124, 5, 1
	s_movk_i32 s13, 0x80
	v_lshl_add_u64 v[6:7], v[6:7], 0, v[116:117]
	s_mov_b64 s[10:11], 0x4e000
	v_lshrrev_b32_e32 v3, 2, v124
	v_and_b32_e32 v2, 31, v124
	v_cmp_gt_i32_e64 s[38:39], s13, v124
	s_lshl_b32 s13, s12, 1
	s_mul_i32 s14, s12, 0xc000
	v_lshl_add_u64 v[82:83], v[6:7], 0, s[10:11]
	v_bfe_u32 v5, v124, 2, 2
	v_and_b32_e32 v6, 0xffffffc0, v97
	v_bitop3_b32 v3, v1, v3, 3 bitop3:0x78
	s_mul_hi_u32 s13, s13, 0x6000
	v_or_b32_e32 v7, v6, v2
	v_lshlrev_b32_e32 v99, 4, v3
	v_bitop3_b32 v3, v1, v5, 2 bitop3:0x36
	s_add_u32 s10, s2, s14
	v_ashrrev_i32_e32 v125, 31, v124
	v_lshlrev_b32_e32 v95, 6, v7
	v_lshlrev_b32_e32 v7, 6, v124
	v_lshlrev_b32_e32 v100, 4, v3
	v_mov_b32_e32 v3, 0x11000
	s_addc_u32 s11, s3, s13
	v_lshl_add_u64 v[8:9], s[2:3], 0, v[8:9]
	v_and_b32_e32 v98, 0x17c0, v7
	v_lshl_add_u32 v101, v124, 2, v3
	v_lshl_add_u32 v3, v6, 2, v3
	v_ashrrev_i32_e32 v97, 31, v96
	v_lshl_add_u64 v[6:7], v[124:125], 2, s[10:11]
	s_mov_b64 s[10:11], 0x18dce000
	v_and_b32_e32 v4, 64, v124
	v_lshl_add_u64 v[8:9], v[8:9], 0, v[116:117]
	s_mov_b64 s[16:17], 0x96ce000
	v_lshlrev_b32_e32 v1, 4, v1
	v_lshl_add_u64 v[84:85], v[6:7], 0, s[10:11]
	s_add_u32 s10, s2, 0x18dfe000
	v_lshl_add_u64 v[6:7], v[96:97], 1, s[2:3]
	s_mov_b64 s[14:15], 0xf6ce000
	v_lshl_add_u64 v[80:81], v[8:9], 0, s[16:17]
	v_lshlrev_b32_e32 v94, 11, v126
	s_addc_u32 s11, s3, 0
	v_lshl_add_u64 v[86:87], v[6:7], 0, s[14:15]
	s_mov_b64 s[16:17], 0
	s_mov_b64 s[14:15], 0
	v_lshlrev_b32_e32 v88, 2, v4
	v_lshlrev_b32_e32 v90, 2, v2
	v_add_u32_e32 v96, v3, v1
	s_branch .LBB0_259

.LBB0_263:
	s_or_b64 exec, exec, s[18:19]
	s_mov_b64 s[18:19], src_shared_base
	v_mov_b32_e32 v121, s19
	s_waitcnt lgkmcnt(0)
	s_barrier
	flat_load_dword v103, v[120:121] sc0 sc1
	s_waitcnt vmcnt(0)
	s_cmp_eq_u32 s98, 0
	s_cbranch_scc1 .Lgq_skip2
	v_mul_u32_u24_e32 v1, 0xaaab, v103
	v_lshrrev_b32_e32 v1, 18, v1
	v_mul_u32_u24_e32 v2, 6, v1
	v_sub_u32_e32 v2, v103, v2
	v_mul_u32_u24_e32 v1, 48, v1
	v_lshl_add_u32 v1, v2, 3, v1
	v_add_u32_e32 v1, s99, v1
	v_add_u32_e32 v2, 0x600, v103
	s_movk_i32 s13, 0xc0
	v_cmp_gt_u32_e64 s[18:19], s13, v103
	s_nop 1
	v_cndmask_b32_e64 v103, v2, v1, s[18:19]
.Lgq_skip2:
	s_movk_i32 s13, 0x600
	s_xor_b64 s[16:17], s[16:17], -1
	s_waitcnt lgkmcnt(0)
	v_cmp_gt_u32_e64 s[42:43], s13, v103
	s_movk_i32 s13, 0x5ff
	v_cmp_lt_u32_e64 s[40:41], s13, v103
	s_and_saveexec_b64 s[18:19], s[42:43]
	s_mov_b32 s13, 0xaaab
	v_mul_u32_u24_sdwa v1, v103, s13 dst_sel:DWORD dst_unused:UNUSED_PAD src0_sel:WORD_0 src1_sel:DWORD
	v_lshrrev_b32_e32 v1, 21, v1
	v_mul_lo_u16_e32 v2, 48, v1
	v_sub_u16_e32 v2, v103, v2
	v_lshlrev_b16_e32 v1, 7, v1
	v_lshlrev_b16_e32 v97, 7, v2
	v_add_u16_e32 v102, 0xe00, v1
	s_or_b64 exec, exec, s[18:19]
	s_mov_b32 s13, 0xaaab
	v_mul_u32_u24_sdwa v1, v0, s13 dst_sel:DWORD dst_unused:UNUSED_PAD src0_sel:WORD_0 src1_sel:DWORD
	v_lshrrev_b32_e32 v1, 21, v1
	v_mul_lo_u16_e32 v2, 48, v1
	v_sub_u16_e32 v0, v0, v2
	v_lshlrev_b16_e32 v92, 7, v0
	v_mov_b32_e32 v73, 0x358637bd
	s_and_saveexec_b64 s[18:19], s[38:39]
	s_cbranch_execz .LBB0_267
	v_lshlrev_b32_e32 v116, 2, v92
	v_lshl_add_u64 v[2:3], v[84:85], 0, v[116:117]
	global_load_dword v2, v[2:3], off
	s_waitcnt vmcnt(0)
	v_cvt_f32_u32_e32 v2, v2
	v_fmamk_f32 v73, v2, 0x36800000, v212

.Llb_chk:
	s_cmp_eq_u32 s99, 2
	s_cbranch_scc1 .Llb_do
	s_cmp_eq_u32 s99, 4
	s_cbranch_scc1 .Llb_do
	s_cmp_eq_u32 s99, 5
	s_cbranch_scc0 .LBB0_509
